# v65 + MLA unit prologue: the second query half's three Q-row loads also issued at the top of the prologue (free VGPRs, moved into place)
# baseline (speedup 1.0000x reference)
.LBB0_652:
	v_add_u32_e32 v156, s40, v139
	s_mul_i32 s40, s55, 0x60
	v_mov_b64_e32 v[2:3], s[14:15]
	s_ashr_i32 s41, s40, 31
	v_mad_i64_i32 v[2:3], s[12:13], v156, s19, v[2:3]
	v_lshl_add_u64 v[2:3], s[40:41], 1, v[2:3]
	v_lshlrev_b32_e32 v0, 1, v138
	v_lshl_add_u64 v[2:3], v[2:3], 0, v[0:1]
	s_lshl_b64 s[56:57], s[40:41], 1
	s_add_u32 s60, s48, s56
	s_addc_u32 s61, s49, s57
	v_lshlrev_b64 v[246:247], 1, v[146:147]
	v_lshlrev_b64 v[248:249], 1, v[148:149]
	v_lshl_add_u64 v[246:247], v[140:141], 1, v[246:247]
	v_lshl_add_u64 v[248:249], v[142:143], 1, v[248:249]
	v_lshl_add_u64 v[246:247], s[60:61], 0, v[246:247]
	v_lshl_add_u64 v[248:249], s[60:61], 0, v[248:249]
	s_lshl_b32 s56, s55, 6
	s_ashr_i32 s57, s56, 31
	s_lshl_b64 s[56:57], s[56:57], 1
	v_lshl_add_u64 v[250:251], s[52:53], 0, v[150:151]
	v_lshl_add_u64 v[250:251], v[250:251], 0, s[56:57]
	v_lshl_add_u64 v[250:251], v[250:251], 0, v[152:153]
	global_load_dwordx4 v[234:237], v[246:247], off
	global_load_dwordx4 v[238:241], v[248:249], off
	global_load_dwordx4 v[242:245], v[250:251], off
	s_lshl_b32 s56, s19, 4
	s_ashr_i32 s57, s56, 31
	v_lshl_add_u64 v[224:225], v[2:3], 0, s[56:57]
	global_load_dwordx4 v[220:223], v[224:225], off
	global_load_dwordx4 v[228:231], v[224:225], off offset:64
	global_load_dwordx4 v[246:249], v[224:225], off offset:128
	global_load_dwordx4 v[18:21], v[2:3], off
	global_load_dwordx4 v[22:25], v[2:3], off offset:64
	global_load_dwordx4 v[44:47], v[2:3], off offset:128
	s_nop 0
	global_load_dwordx4 v[2:5], v[144:145], off offset:16
	global_load_dwordx4 v[10:13], v[144:145], off
	global_load_dwordx4 v[48:51], v[144:145], off offset:272
	global_load_dwordx4 v[52:55], v[144:145], off offset:256
	global_load_dwordx4 v[6:9], v[144:145], off offset:144
	global_load_dwordx4 v[14:17], v[144:145], off offset:128
	s_waitcnt vmcnt(28)
	v_and_b32_e32 v27, 64, v232
	v_xor_b32_e32 v26, 16, v232
	s_waitcnt vmcnt(24)
	v_add_u32_e32 v43, 64, v27
	v_cmp_lt_i32_e32 vcc, v26, v43
	v_ashrrev_i32_e32 v157, 31, v156
	s_waitcnt vmcnt(8)
	v_and_b32_e32 v41, 0xffff0000, v18
	v_cndmask_b32_e32 v26, v232, v26, vcc
	v_lshlrev_b32_e32 v155, 2, v26
	v_lshlrev_b32_e32 v42, 16, v18
	v_mul_f32_e32 v26, v41, v41
	v_lshlrev_b32_e32 v40, 16, v19
	v_fmac_f32_e32 v26, v42, v42
	v_and_b32_e32 v39, 0xffff0000, v19
	v_fmac_f32_e32 v26, v40, v40
	v_lshlrev_b32_e32 v38, 16, v20
	v_fmac_f32_e32 v26, v39, v39
	v_and_b32_e32 v37, 0xffff0000, v20
	v_fmac_f32_e32 v26, v38, v38
	v_lshlrev_b32_e32 v36, 16, v21
	v_fmac_f32_e32 v26, v37, v37
	v_and_b32_e32 v35, 0xffff0000, v21
	v_fmac_f32_e32 v26, v36, v36
	s_waitcnt vmcnt(7)
	v_lshlrev_b32_e32 v34, 16, v22
	v_fmac_f32_e32 v26, v35, v35
	v_and_b32_e32 v33, 0xffff0000, v22
	v_fmac_f32_e32 v26, v34, v34
	v_lshlrev_b32_e32 v32, 16, v23
	v_fmac_f32_e32 v26, v33, v33
	v_and_b32_e32 v31, 0xffff0000, v23
	v_fmac_f32_e32 v26, v32, v32
	v_lshlrev_b32_e32 v30, 16, v24
	v_fmac_f32_e32 v26, v31, v31
	v_and_b32_e32 v29, 0xffff0000, v24
	v_fmac_f32_e32 v26, v30, v30
	v_lshlrev_b32_e32 v28, 16, v25
	v_fmac_f32_e32 v26, v29, v29
	v_and_b32_e32 v27, 0xffff0000, v25
	s_waitcnt vmcnt(6)
	v_and_b32_e32 v25, 0xffff0000, v44
	v_lshlrev_b32_e32 v24, 16, v44
	v_fmac_f32_e32 v26, v28, v28
	v_pk_mul_f32 v[58:59], v[24:25], v[24:25]
	v_fmac_f32_e32 v26, v27, v27
	v_and_b32_e32 v23, 0xffff0000, v45
	v_lshlrev_b32_e32 v22, 16, v45
	v_add_f32_e32 v26, v58, v26
	v_pk_mul_f32 v[56:57], v[22:23], v[22:23]
	v_add_f32_e32 v26, v59, v26
	v_and_b32_e32 v21, 0xffff0000, v46
	v_lshlrev_b32_e32 v20, 16, v46
	v_add_f32_e32 v26, v56, v26
	v_and_b32_e32 v19, 0xffff0000, v47
	v_lshlrev_b32_e32 v18, 16, v47
	v_pk_mul_f32 v[46:47], v[20:21], v[20:21]
	v_add_f32_e32 v26, v57, v26
	v_add_f32_e32 v26, v46, v26
	v_pk_mul_f32 v[44:45], v[18:19], v[18:19]
	v_add_f32_e32 v26, v47, v26
	v_add_f32_e32 v26, v44, v26
	v_add_f32_e32 v26, v45, v26
	ds_bpermute_b32 v44, v155, v26
	v_xor_b32_e32 v45, 32, v232
	v_cmp_lt_i32_e32 vcc, v45, v43
	s_waitcnt lgkmcnt(0)
	v_add_f32_e32 v26, v26, v44
	v_cndmask_b32_e32 v43, v232, v45, vcc
	v_lshlrev_b32_e32 v176, 2, v43
	ds_bpermute_b32 v43, v176, v26
	v_cndmask_b32_e64 v44, 0, 1, s[70:71]
	v_cmp_ne_u32_e64 s[12:13], 1, v44
	s_andn2_b64 vcc, exec, s[70:71]
	s_waitcnt lgkmcnt(0)
	v_add_f32_e32 v26, v26, v43
	v_fmamk_f32 v26, v26, 0x3c2aaaab, v227
	v_rsq_f32_e32 v26, v26
	s_nop 0
	v_pk_mul_f32 v[24:25], v[26:27], v[24:25] op_sel_hi:[0,1]
	v_pk_mul_f32 v[22:23], v[26:27], v[22:23] op_sel_hi:[0,1]
	v_pk_mul_f32 v[20:21], v[26:27], v[20:21] op_sel_hi:[0,1]
	v_pk_mul_f32 v[18:19], v[26:27], v[18:19] op_sel_hi:[0,1]
	s_waitcnt vmcnt(2)
	v_pk_mul_f32 v[24:25], v[52:53], v[24:25]
	v_pk_mul_f32 v[22:23], v[54:55], v[22:23]
	v_pk_mul_f32 v[20:21], v[48:49], v[20:21]
	v_pk_mul_f32 v[18:19], v[50:51], v[18:19]
	s_cbranch_vccnz .LBB0_654
	v_and_b32_e32 v43, 63, v156
	v_bfe_u32 v44, v156, 6, 4
	v_cndmask_b32_e64 v43, v43, v44, s[8:9]
	v_lshlrev_b32_e32 v43, 6, v43
	global_load_dwordx4 v[44:47], v43, s[26:27] offset:48
	global_load_dwordx4 v[48:51], v43, s[26:27] offset:32
	global_load_dwordx4 v[52:55], v43, s[26:27] offset:16
	global_load_dwordx4 v[56:59], v43, s[26:27]
	ds_bpermute_b32 v60, v155, v24
	ds_bpermute_b32 v61, v155, v25
	s_waitcnt vmcnt(0)
	v_mov_b32_e32 v63, v58
	v_mov_b32_e32 v58, v57
	v_mov_b32_e32 v62, v56
	s_waitcnt lgkmcnt(0)
	v_pk_mul_f32 v[56:57], v[58:59], v[60:61]
	v_mov_b32_e32 v59, v54
	v_cndmask_b32_e64 v57, v57, -v57, s[10:11]
	v_cndmask_b32_e64 v56, v56, -v56, s[10:11]
	v_pk_fma_f32 v[24:25], v[24:25], v[62:63], v[56:57]
	ds_bpermute_b32 v56, v155, v22
	ds_bpermute_b32 v57, v155, v23
	v_mov_b32_e32 v54, v53
	v_mov_b32_e32 v58, v52
	s_waitcnt lgkmcnt(0)
	v_pk_mul_f32 v[52:53], v[54:55], v[56:57]
	s_nop 0
	v_cndmask_b32_e64 v53, v53, -v53, s[10:11]
	v_cndmask_b32_e64 v52, v52, -v52, s[10:11]
	v_pk_fma_f32 v[22:23], v[22:23], v[58:59], v[52:53]
	ds_bpermute_b32 v52, v155, v20
	ds_bpermute_b32 v53, v155, v21
	v_mov_b32_e32 v55, v50
	v_mov_b32_e32 v50, v49
	v_mov_b32_e32 v54, v48
	s_waitcnt lgkmcnt(0)
	v_pk_mul_f32 v[48:49], v[50:51], v[52:53]
	s_nop 0
	v_cndmask_b32_e64 v49, v49, -v49, s[10:11]
	v_cndmask_b32_e64 v48, v48, -v48, s[10:11]
	v_pk_fma_f32 v[20:21], v[20:21], v[54:55], v[48:49]
	ds_bpermute_b32 v48, v155, v18
	ds_bpermute_b32 v49, v155, v19
	v_mov_b32_e32 v51, v46
	v_mov_b32_e32 v46, v45
	v_mov_b32_e32 v50, v44
	s_waitcnt lgkmcnt(0)
	v_pk_mul_f32 v[44:45], v[46:47], v[48:49]
	s_nop 0
	v_cndmask_b32_e64 v45, v45, -v45, s[10:11]
	v_cndmask_b32_e64 v44, v44, -v44, s[10:11]
	v_pk_fma_f32 v[18:19], v[18:19], v[50:51], v[44:45]
.LBB0_654:
	v_mul_f32_e32 v38, v26, v38
	v_mul_f32_e32 v38, v2, v38
	v_mul_f32_e32 v2, v26, v37
	v_mul_f32_e32 v37, v3, v2
	v_mul_f32_e32 v2, v26, v36
	v_mul_f32_e32 v36, v4, v2
	v_mul_f32_e32 v2, v26, v35
	v_mul_f32_e32 v5, v5, v2
	v_mul_f32_e32 v2, v26, v34
	s_waitcnt vmcnt(0)
	v_mul_f32_e32 v14, v14, v2
	v_mul_f32_e32 v2, v26, v33
	v_mul_f32_e32 v15, v15, v2
	v_mul_f32_e32 v2, v26, v32
	v_mul_f32_e32 v16, v16, v2
	v_mul_f32_e32 v2, v26, v31
	v_mul_f32_e32 v17, v17, v2
	v_mul_f32_e32 v2, v26, v30
	v_mul_f32_e32 v30, v6, v2
	v_mul_f32_e32 v2, v26, v29
	v_mul_f32_e32 v29, v7, v2
	v_mul_f32_e32 v2, v26, v28
	v_mul_f32_e32 v42, v26, v42
	v_mul_f32_e32 v41, v26, v41
	v_mul_f32_e32 v40, v26, v40
	v_mul_f32_e32 v39, v26, v39
	v_mul_f32_e32 v28, v8, v2
	v_mul_f32_e32 v2, v26, v27
	v_mul_f32_e32 v10, v10, v42
	v_mul_f32_e32 v11, v11, v41
	v_mul_f32_e32 v12, v12, v40
	v_mul_f32_e32 v13, v13, v39
	v_mul_f32_e32 v9, v9, v2
	v_cvt_pk_bf16_f32 v2, v10, v11
	v_cvt_pk_bf16_f32 v3, v12, v13
	v_cvt_pk_bf16_f32 v4, v38, v37
	v_cvt_pk_bf16_f32 v5, v36, v5
	v_cvt_pk_bf16_f32 v6, v14, v15
	v_add_u32_e32 v158, 16, v156
	v_mov_b64_e32 v[14:15], s[14:15]
	v_mad_i64_i32 v[14:15], s[56:57], v158, s19, v[14:15]
	v_lshl_add_u64 v[14:15], s[40:41], 1, v[14:15]
	v_lshl_add_u64 v[14:15], v[14:15], 0, v[0:1]
	v_cvt_pk_bf16_f32 v7, v16, v17
	v_cvt_pk_bf16_f32 v8, v30, v29
	v_cvt_pk_bf16_f32 v9, v28, v9
	v_cvt_pk_bf16_f32 v10, v24, v25
	v_cvt_pk_bf16_f32 v11, v22, v23
	v_cvt_pk_bf16_f32 v12, v20, v21
	v_cvt_pk_bf16_f32 v13, v18, v19
	v_mov_b64_e32 v[30:31], v[220:221]
	v_mov_b64_e32 v[32:33], v[222:223]
	v_mov_b64_e32 v[34:35], v[228:229]
	v_mov_b64_e32 v[36:37], v[230:231]
	v_mov_b64_e32 v[54:55], v[246:247]
	v_mov_b64_e32 v[56:57], v[248:249]
	global_load_dwordx4 v[58:61], v[144:145], off offset:272
	global_load_dwordx4 v[62:65], v[144:145], off offset:256
	global_load_dwordx4 v[22:25], v[144:145], off offset:16
	global_load_dwordx4 v[26:29], v[144:145], off
	s_nop 0
	global_load_dwordx4 v[14:17], v[144:145], off offset:144
	global_load_dwordx4 v[18:21], v[144:145], off offset:128
	s_and_b64 vcc, exec, s[12:13]
	v_ashrrev_i32_e32 v159, 31, v158
	s_waitcnt vmcnt(8)
	v_and_b32_e32 v52, 0xffff0000, v30
	v_lshlrev_b32_e32 v53, 16, v30
	v_mul_f32_e32 v0, v52, v52
	v_lshlrev_b32_e32 v51, 16, v31
	v_fmac_f32_e32 v0, v53, v53
	v_and_b32_e32 v50, 0xffff0000, v31
	v_fmac_f32_e32 v0, v51, v51
	v_lshlrev_b32_e32 v49, 16, v32
	v_fmac_f32_e32 v0, v50, v50
	v_and_b32_e32 v48, 0xffff0000, v32
	v_fmac_f32_e32 v0, v49, v49
	v_lshlrev_b32_e32 v47, 16, v33
	v_fmac_f32_e32 v0, v48, v48
	v_and_b32_e32 v46, 0xffff0000, v33
	v_fmac_f32_e32 v0, v47, v47
	s_waitcnt vmcnt(7)
	v_lshlrev_b32_e32 v45, 16, v34
	v_fmac_f32_e32 v0, v46, v46
	v_and_b32_e32 v44, 0xffff0000, v34
	v_fmac_f32_e32 v0, v45, v45
	v_lshlrev_b32_e32 v43, 16, v35
	v_fmac_f32_e32 v0, v44, v44
	v_and_b32_e32 v42, 0xffff0000, v35
	v_fmac_f32_e32 v0, v43, v43
	v_lshlrev_b32_e32 v41, 16, v36
	v_fmac_f32_e32 v0, v42, v42
	v_and_b32_e32 v40, 0xffff0000, v36
	v_fmac_f32_e32 v0, v41, v41
	v_lshlrev_b32_e32 v39, 16, v37
	v_fmac_f32_e32 v0, v40, v40
	v_and_b32_e32 v38, 0xffff0000, v37
	s_waitcnt vmcnt(6)
	v_and_b32_e32 v37, 0xffff0000, v54
	v_fmac_f32_e32 v0, v39, v39
	v_lshlrev_b32_e32 v36, 16, v54
	v_and_b32_e32 v35, 0xffff0000, v55
	v_lshlrev_b32_e32 v34, 16, v55
	v_fmac_f32_e32 v0, v38, v38
	v_pk_mul_f32 v[54:55], v[36:37], v[36:37]
	v_pk_mul_f32 v[68:69], v[34:35], v[34:35]
	v_add_f32_e32 v0, v54, v0
	v_add_f32_e32 v0, v55, v0
	v_and_b32_e32 v33, 0xffff0000, v56
	v_lshlrev_b32_e32 v32, 16, v56
	v_add_f32_e32 v0, v68, v0
	v_pk_mul_f32 v[66:67], v[32:33], v[32:33]
	v_add_f32_e32 v0, v69, v0
	v_and_b32_e32 v31, 0xffff0000, v57
	v_lshlrev_b32_e32 v30, 16, v57
	v_add_f32_e32 v0, v66, v0
	v_pk_mul_f32 v[56:57], v[30:31], v[30:31]
	v_add_f32_e32 v0, v67, v0
	v_add_f32_e32 v0, v56, v0
	v_add_f32_e32 v0, v57, v0
	ds_bpermute_b32 v54, v155, v0
	s_waitcnt lgkmcnt(0)
	v_add_f32_e32 v0, v0, v54
	ds_bpermute_b32 v54, v176, v0
	s_waitcnt lgkmcnt(0)
	v_add_f32_e32 v0, v0, v54
	v_fmamk_f32 v0, v0, 0x3c2aaaab, v227
	v_rsq_f32_e32 v0, v0
	s_nop 0
	v_pk_mul_f32 v[36:37], v[0:1], v[36:37] op_sel_hi:[0,1]
	v_pk_mul_f32 v[34:35], v[0:1], v[34:35] op_sel_hi:[0,1]
	v_pk_mul_f32 v[32:33], v[0:1], v[32:33] op_sel_hi:[0,1]
	v_pk_mul_f32 v[30:31], v[0:1], v[30:31] op_sel_hi:[0,1]
	s_waitcnt vmcnt(4)
	v_pk_mul_f32 v[36:37], v[62:63], v[36:37]
	v_pk_mul_f32 v[34:35], v[64:65], v[34:35]
	v_pk_mul_f32 v[32:33], v[58:59], v[32:33]
	v_pk_mul_f32 v[30:31], v[60:61], v[30:31]
	s_cbranch_vccnz .LBB0_656
	v_and_b32_e32 v54, 63, v158
	v_bfe_u32 v55, v158, 6, 4
	v_cndmask_b32_e64 v54, v54, v55, s[8:9]
	v_lshlrev_b32_e32 v66, 6, v54
	global_load_dwordx4 v[54:57], v66, s[26:27] offset:48
	global_load_dwordx4 v[58:61], v66, s[26:27] offset:32
	global_load_dwordx4 v[62:65], v66, s[26:27] offset:16
	s_nop 0
	global_load_dwordx4 v[66:69], v66, s[26:27]
	ds_bpermute_b32 v70, v155, v36
	ds_bpermute_b32 v71, v155, v37
	s_waitcnt vmcnt(0)
	v_mov_b32_e32 v73, v68
	v_mov_b32_e32 v68, v67
	v_mov_b32_e32 v72, v66
	s_waitcnt lgkmcnt(0)
	v_pk_mul_f32 v[66:67], v[68:69], v[70:71]
	v_mov_b32_e32 v69, v64
	v_cndmask_b32_e64 v67, v67, -v67, s[10:11]
	v_cndmask_b32_e64 v66, v66, -v66, s[10:11]
	v_pk_fma_f32 v[36:37], v[36:37], v[72:73], v[66:67]
	ds_bpermute_b32 v66, v155, v34
	ds_bpermute_b32 v67, v155, v35
	v_mov_b32_e32 v64, v63
	v_mov_b32_e32 v68, v62
	s_waitcnt lgkmcnt(0)
	v_pk_mul_f32 v[62:63], v[64:65], v[66:67]
	s_nop 0
	v_cndmask_b32_e64 v63, v63, -v63, s[10:11]
	v_cndmask_b32_e64 v62, v62, -v62, s[10:11]
	v_pk_fma_f32 v[34:35], v[34:35], v[68:69], v[62:63]
	ds_bpermute_b32 v62, v155, v32
	ds_bpermute_b32 v63, v155, v33
	v_mov_b32_e32 v65, v60
	v_mov_b32_e32 v60, v59
	v_mov_b32_e32 v64, v58
	s_waitcnt lgkmcnt(0)
	v_pk_mul_f32 v[58:59], v[60:61], v[62:63]
	s_nop 0
	v_cndmask_b32_e64 v59, v59, -v59, s[10:11]
	v_cndmask_b32_e64 v58, v58, -v58, s[10:11]
	v_pk_fma_f32 v[32:33], v[32:33], v[64:65], v[58:59]
	ds_bpermute_b32 v58, v155, v30
	ds_bpermute_b32 v59, v155, v31
	v_mov_b32_e32 v61, v56
	v_mov_b32_e32 v56, v55
	v_mov_b32_e32 v60, v54
	s_waitcnt lgkmcnt(0)
	v_pk_mul_f32 v[54:55], v[56:57], v[58:59]
	s_nop 0
	v_cndmask_b32_e64 v55, v55, -v55, s[10:11]
	v_cndmask_b32_e64 v54, v54, -v54, s[10:11]
	v_pk_fma_f32 v[30:31], v[30:31], v[60:61], v[54:55]
